# P2d overlapped with P5 GEMM#1-#2 across workgroups: even WGs run the two GEMMs first, odd WGs P2d first; seam 4 moved between {P2d,GEMM#1-2} and GEMM#3-4
# speedup vs baseline: 1.0112x; 1.0014x over previous
; __global__ void __launch_bounds__(512, 2) hybrid_fwd(Args args) {
;     ...
;     DUP_BEGIN(3) if (IN(3)) {
;         if (sub & 1) for (int cu = F.bid; cu < 1024; cu += F.G) {
;             if (cu < 512) conv_unit<16384, 1>(F, cu, FRS, F0 + 1024, args.in[15], UT, UT, TOKP, dry);
;             else conv_unit<4096, 4>(F, cu - 512, FRP, F0, args.in[15], UT, UT, 0, dry);
;         }
.LBB0_753:
	v_mov_b32_e32 v255, 0
	v_mov_b32_e32 v247, 1
	s_cmp_lt_i32 s84, 4
	s_cselect_b64 s[2:3], -1, 0
	s_and_b64 s[0:1], s[2:3], s[0:1]
	v_writelane_b32 v246, s0, 34
	s_andn2_b64 vcc, exec, s[0:1]
	s_nop 0
	v_writelane_b32 v246, s1, 35
	s_cbranch_vccnz .LBB0_1110
	v_writelane_b32 v246, s96, 30
	s_cmpk_gt_i32 s33, 0x3ff
	s_nop 0
	v_writelane_b32 v246, s97, 31
	v_writelane_b32 v246, s87, 36
	v_writelane_b32 v246, s94, 37
	s_nop 1
	v_writelane_b32 v246, s95, 38
	v_writelane_b32 v246, s84, 39
	s_nop 1
	v_writelane_b32 v246, s85, 40
	s_cbranch_scc1 .LBB0_1054
	v_mov_b32_e32 v247, 0
	s_bitcmp1_b32 s33, 0
	s_cbranch_scc1 .LBB0_1054

; __global__ void __launch_bounds__(512, 2) hybrid_fwd(Args args) {
;     ...
;     SEAM(3);
;     DUP_BEGIN(4) if (IN(4)) { for (int u = F.bid; u < 2048; u += F.G) p2d_unit(F, u, HY, UT, Kb, args.in[5], args.in[6]); }
.LBB0_1164:
	v_cmp_ne_u32_e32 vcc, 0, v255
	s_cbranch_vccnz .Lx_h1_done
	s_bitcmp1_b32 s33, 0
	s_cbranch_scc1 .Lx_h1_odd
	v_mov_b32_e32 v255, 1
	s_mov_b64 s[0:1], -1
	s_branch .LBB0_1229
.Lx_h1_odd:
	v_mov_b32_e32 v255, 3

; __global__ void __launch_bounds__(512, 2) hybrid_fwd(Args args) {
;     ...
;     DUP_BEGIN(4) if (IN(4)) { for (int u = F.bid; u < 2048; u += F.G) p2d_unit(F, u, HY, UT, Kb, args.in[5], args.in[6]); }
;     DUP_END(4)
;     SEAM(4);
.LBB0_1175:
	v_cmp_eq_u32_e32 vcc, 3, v255
	s_cbranch_vccz .Lx_h2_done
	v_mov_b32_e32 v255, 4
	s_mov_b64 s[0:1], -1
	s_branch .LBB0_1229

; __global__ void __launch_bounds__(512, 2) hybrid_fwd(Args args) {
;     ...
;     DUP_BEGIN(5) if (IN(5)) {
;         pg8::StaticOrder S; S.init(MTOK, DM, F.G, F.bid);
;         { pg8::Gemm g{XB, WIN + (size_t)3072 * DM, MTOK, DM, DM}; EpiGate E{M1, SS0}; pg8::gemm_phase<EpiGate, pg8::StaticOrder, true, true>(F.lds, g, S, E); }
;         { pg8::Gemm g{Qb, WBA, MTOK, DM, 512}; EpiMix<0> E{M1, nullptr}; pg8::gemm_phase<EpiMix<0>, pg8::StaticOrder, true, true>(F.lds, g, S, E); }
.LBB0_1229:
	v_cmp_eq_u32_e32 vcc, 2, v255
	s_cbranch_vccnz .Lx_h4_go
	v_cmp_eq_u32_e32 vcc, 5, v255
	s_cbranch_vccz .Lx_h4_done
.Lx_h4_go:
	v_mov_b32_e32 v255, 9
	s_mov_b64 s[2:3], 0
	s_mov_b64 s[14:15], -1
	s_branch .LBB0_1278
	s_nop 0
	s_nop 0
	s_nop 0
	s_nop 0
	s_nop 0
	s_nop 0
	s_nop 0
	s_nop 0
	s_nop 0
	s_nop 0

; __global__ void __launch_bounds__(512, 2) hybrid_fwd(Args args) {
;     ...
;     DUP_BEGIN(4) if (IN(4)) { for (int u = F.bid; u < 2048; u += F.G) p2d_unit(F, u, HY, UT, Kb, args.in[5], args.in[6]); }
;     ...
;         { pg8::Gemm g{XB, WIN + (size_t)3072 * DM, MTOK, DM, DM}; EpiGate E{M1, SS0}; pg8::gemm_phase<EpiGate, pg8::StaticOrder, true, true>(F.lds, g, S, E); }
;         { pg8::Gemm g{Qb, WBA, MTOK, DM, 512}; EpiMix<0> E{M1, nullptr}; pg8::gemm_phase<EpiMix<0>, pg8::StaticOrder, true, true>(F.lds, g, S, E); }
;         { pg8::Gemm g{XB, WIN + (size_t)4096 * DM, MTOK, DM, DM}; EpiGate E{M2, SS0}; pg8::gemm_phase<EpiGate, pg8::StaticOrder, true, true>(F.lds, g, S, E); }
;         { pg8::Gemm g{Kb, WBH, MTOK, DM, 512}; EpiMix<1> E{M1, M2}; pg8::gemm_phase<EpiMix<1>, pg8::StaticOrder, true, true>(F.lds, g, S, E); }
.LBB0_1278:
	v_cmp_eq_u32_e32 vcc, 1, v255
	s_cbranch_vccz .Lx_h3_a
	v_mov_b32_e32 v255, 2
	s_add_u32 s60, s80, 0x6000000
	s_addc_u32 s61, s81, 0
	v_lshlrev_b32_e32 v152, 3, v150
	s_mov_b64 s[0:1], -1
	s_branch .LBB0_1164
.Lx_h3_a:
	v_cmp_eq_u32_e32 vcc, 4, v255
	s_cbranch_vccz .Lx_h3_done
	v_mov_b32_e32 v255, 5
	s_mov_b64 s[2:3], -1
	s_branch .LBB0_1175
	s_nop 0
	s_nop 0
